# attention: remap (b,h) so the 4 q-heads sharing a kv head run on one XCD; nt hints on Q loads and Y stores
# baseline (speedup 1.0000x reference)
.LBB0_422:
	s_lshr_b32 s100, s87, 3
	s_and_b32 s63, s100, 3
	s_lshl_b32 s63, s63, 2
	s_bfe_u32 s101, s100, 0x20003
	s_or_b32 s63, s63, s101
	s_lshr_b32 s89, s100, 5
	s_lshl_b32 s89, s89, 1
	s_bfe_u32 s101, s100, 0x10002
	s_or_b32 s89, s89, s101
	v_mbcnt_lo_u32_b32 v4, -1, 0
	v_mbcnt_hi_u32_b32 v4, -1, v4
	s_lshl_b32 s88, s89, 11
	v_and_b32_e32 v5, 31, v4
	s_mul_i32 s89, s89, 20
	v_or_b32_e32 v0, s88, v5
	s_add_i32 s0, s89, s63
	v_ashrrev_i32_e32 v1, 31, v0
	s_add_i32 s0, s0, 4
	v_ashrrev_i32_e32 v6, 5, v4
	v_lshlrev_b64 v[0:1], 12, v[0:1]
	s_ashr_i32 s1, s0, 31
	v_lshl_add_u64 v[0:1], s[48:49], 0, v[0:1]
	s_lshl_b32 s33, s63, 6
	s_lshl_b32 s56, s63, 7
	v_lshlrev_b32_e32 v2, 3, v6
	s_lshl_b64 s[0:1], s[0:1], 18
	v_lshl_add_u64 v[0:1], v[0:1], 0, s[56:57]
	s_waitcnt lgkmcnt(0)
	v_ashrrev_i32_e32 v3, 31, v2
	s_add_u32 s4, s52, s0
	s_waitcnt vmcnt(11)
	v_lshl_add_u64 v[128:129], v[2:3], 1, v[0:1]
	s_addc_u32 s5, s53, s1
	v_lshl_add_u64 v[0:1], v[128:129], 0, s[64:65]
	s_add_u32 s0, s58, s0
	global_load_dwordx4 v[48:51], v[0:1], off offset:2048 nt
	global_load_dwordx4 v[52:55], v[0:1], off offset:2080 nt
	global_load_dwordx4 v[56:59], v[0:1], off offset:2112 nt
	global_load_dwordx4 v[60:63], v[0:1], off offset:2144 nt
	s_addc_u32 s1, s59, s1
	v_lshlrev_b32_e32 v0, 3, v4
	s_add_u32 s6, s4, s60
	v_ashrrev_i32_e32 v1, 31, v0
	s_addc_u32 s7, s5, 0
	v_lshlrev_b64 v[0:1], 1, v[0:1]
	v_lshl_add_u64 v[2:3], s[6:7], 0, v[0:1]
	v_lshl_add_u64 v[130:131], s[0:1], 0, v[0:1]
	global_load_dwordx4 v[64:67], v[2:3], off
	global_load_dwordx4 v[68:71], v[2:3], off offset:1024
	global_load_dwordx4 v[72:75], v[2:3], off offset:2048
	global_load_dwordx4 v[80:83], v[2:3], off offset:3072
	v_lshl_add_u64 v[2:3], v[130:131], 0, s[60:61]
	global_load_dwordx4 v[76:79], v[2:3], off
	global_load_dwordx4 v[84:87], v[2:3], off offset:1024
	global_load_dwordx4 v[88:91], v[2:3], off offset:2048
	global_load_dwordx4 v[92:95], v[2:3], off offset:3072
	s_waitcnt vmcnt(22)
	v_lshl_add_u64 v[132:133], s[4:5], 0, v[0:1]
	v_lshlrev_b32_e32 v0, 4, v4
	v_and_b32_e32 v8, 0xfffffe00, v0
	v_ashrrev_i32_e32 v0, 3, v4
	v_and_b32_e32 v1, 7, v4
	v_add_u32_e32 v2, 8, v0
	v_lshlrev_b32_e32 v160, 4, v1
	v_cmp_eq_u32_e64 s[6:7], 0, v1
	v_ashrrev_i32_e32 v1, 31, v0
	v_ashrrev_i32_e32 v3, 31, v2
	v_lshlrev_b32_e32 v9, 7, v0
	v_lshlrev_b64 v[134:135], 12, v[0:1]
	s_waitcnt vmcnt(21)
	v_lshlrev_b32_e32 v136, 1, v0
	v_lshlrev_b32_e32 v10, 7, v2
	v_lshlrev_b64 v[138:139], 12, v[2:3]
	s_waitcnt vmcnt(20)
	v_lshlrev_b32_e32 v140, 1, v2
	v_add_u32_e32 v2, 16, v0
	v_add_u32_e32 v0, 24, v0
	v_lshlrev_b32_e32 v6, 2, v6
	v_ashrrev_i32_e32 v3, 31, v2
	v_ashrrev_i32_e32 v1, 31, v0
	v_lshlrev_b32_e32 v11, 7, v2
	v_lshlrev_b64 v[142:143], 12, v[2:3]
	s_waitcnt vmcnt(19)
	v_lshlrev_b32_e32 v144, 1, v2
	v_lshlrev_b32_e32 v2, 7, v0
	v_lshlrev_b64 v[146:147], 12, v[0:1]
	s_waitcnt vmcnt(18)
	v_lshlrev_b32_e32 v148, 1, v0
	v_or_b32_e32 v0, 1, v6
	v_cmp_lt_i32_e64 s[10:11], v0, v5
	v_or_b32_e32 v0, 2, v6
	v_cmp_lt_i32_e64 s[12:13], v0, v5
	v_or_b32_e32 v0, 3, v6
	v_cmp_lt_i32_e64 s[14:15], v0, v5
	v_add_u32_e32 v0, 8, v6
	v_cmp_lt_i32_e64 s[16:17], v0, v5
	v_add_u32_e32 v0, 9, v6
	v_cmp_lt_i32_e64 s[18:19], v0, v5
	v_add_u32_e32 v0, 10, v6
	v_cmp_lt_i32_e64 s[20:21], v0, v5
	v_add_u32_e32 v0, 11, v6
	v_cmp_lt_i32_e64 s[22:23], v0, v5
	v_add_u32_e32 v0, 16, v6
	v_cmp_lt_i32_e64 s[24:25], v0, v5
	v_add_u32_e32 v0, 17, v6
	v_cmp_lt_i32_e64 s[26:27], v0, v5
	v_add_u32_e32 v0, 18, v6
	v_cmp_lt_i32_e64 s[28:29], v0, v5
	v_add_u32_e32 v0, 19, v6
	v_cmp_lt_i32_e64 s[30:31], v0, v5
	v_add_u32_e32 v0, 24, v6
	v_cmp_lt_i32_e64 s[34:35], v0, v5
	v_add_u32_e32 v0, 25, v6
	v_cmp_lt_i32_e64 s[36:37], v0, v5
	v_add_u32_e32 v0, 26, v6
	s_add_u32 s94, s84, s56
	v_cmp_gt_u32_e64 s[4:5], 32, v4
	v_lshl_add_u32 v7, v5, 1, s3
	v_add_u32_e32 v4, s3, v160
	v_cmp_lt_i32_e64 s[38:39], v0, v5
	v_add_u32_e32 v0, 27, v6
	s_addc_u32 s95, s85, 0
	v_ashrrev_i32_e32 v137, 31, v136
	v_ashrrev_i32_e32 v141, 31, v140
	v_ashrrev_i32_e32 v145, 31, v144
	v_ashrrev_i32_e32 v149, 31, v148
	v_cmp_lt_i32_e64 s[8:9], v6, v5
	v_cmp_lt_i32_e64 s[40:41], v0, v5
	v_lshl_add_u64 v[150:151], s[94:95], 0, v[160:161]
	v_add_u32_e32 v160, v7, v8
	v_add_u32_e32 v172, v4, v9
	v_add_u32_e32 v173, v4, v10
	v_add_u32_e32 v174, v4, v11
	v_add_u32_e32 v175, v4, v2
	s_mov_b32 s42, s57
	s_branch .LBB0_424

.LBB0_433:
	s_cmp_eq_u32 s42, 7
	s_cbranch_scc1 .LBB0_435
	s_add_i32 s91, s91, 8
	s_and_b32 s56, s91, 0x70
	s_and_b64 s[0:1], s[0:1], exec
	s_cselect_b32 s0, s86, s43
	s_or_b32 s0, s56, s0
	s_lshl_b32 s56, s0, 17
	v_lshl_add_u64 v[32:33], v[128:129], 0, s[56:57]
	s_lshl_b32 s56, s0, 12
	global_load_dwordx4 v[48:51], v[32:33], off offset:2048 nt
	global_load_dwordx4 v[52:55], v[32:33], off offset:2080 nt
	global_load_dwordx4 v[56:59], v[32:33], off offset:2112 nt
	global_load_dwordx4 v[60:63], v[32:33], off offset:2144 nt
	v_lshl_add_u64 v[32:33], v[132:133], 0, s[56:57]
	global_load_dwordx4 v[64:67], v[32:33], off
	global_load_dwordx4 v[68:71], v[32:33], off offset:1024
	global_load_dwordx4 v[72:75], v[32:33], off offset:2048
	global_load_dwordx4 v[80:83], v[32:33], off offset:3072
	v_lshl_add_u64 v[32:33], v[130:131], 0, s[56:57]
	global_load_dwordx4 v[76:79], v[32:33], off
	global_load_dwordx4 v[84:87], v[32:33], off offset:1024
	global_load_dwordx4 v[88:91], v[32:33], off offset:2048
	global_load_dwordx4 v[92:95], v[32:33], off offset:3072
.LBB0_435:
	v_cvt_pk_bf16_f32 v16, v16, v161
	s_nop 2
	ds_write_b16 v160, v16
	v_cvt_pk_bf16_f32 v16, v17, v161
	ds_write_b16 v160, v16 offset:128
	v_cvt_pk_bf16_f32 v16, v18, v161
	ds_write_b16 v160, v16 offset:256
	v_cvt_pk_bf16_f32 v16, v19, v161
	ds_write_b16 v160, v16 offset:384
	v_cvt_pk_bf16_f32 v16, v20, v161
	ds_write_b16 v160, v16 offset:1024
	v_cvt_pk_bf16_f32 v16, v21, v161
	ds_write_b16 v160, v16 offset:1152
	v_cvt_pk_bf16_f32 v16, v22, v161
	ds_write_b16 v160, v16 offset:1280
	v_cvt_pk_bf16_f32 v16, v23, v161
	ds_write_b16 v160, v16 offset:1408
	v_cvt_pk_bf16_f32 v16, v24, v161
	ds_write_b16 v160, v16 offset:2048
	v_cvt_pk_bf16_f32 v16, v25, v161
	ds_write_b16 v160, v16 offset:2176
	v_cvt_pk_bf16_f32 v16, v26, v161
	ds_write_b16 v160, v16 offset:2304
	v_cvt_pk_bf16_f32 v16, v27, v161
	ds_write_b16 v160, v16 offset:2432
	v_cvt_pk_bf16_f32 v16, v28, v161
	ds_write_b16 v160, v16 offset:3072
	v_cvt_pk_bf16_f32 v16, v29, v161
	ds_write_b16 v160, v16 offset:3200
	v_cvt_pk_bf16_f32 v16, v30, v161
	ds_write_b16 v160, v16 offset:3328
	v_cvt_pk_bf16_f32 v16, v31, v161
	ds_write_b16 v160, v16 offset:3456
	v_cvt_pk_bf16_f32 v0, v0, v161
	ds_write_b16 v160, v0 offset:64
	v_cvt_pk_bf16_f32 v0, v1, v161
	ds_write_b16 v160, v0 offset:192
	v_cvt_pk_bf16_f32 v0, v2, v161
	ds_write_b16 v160, v0 offset:320
	v_cvt_pk_bf16_f32 v0, v3, v161
	ds_write_b16 v160, v0 offset:448
	v_cvt_pk_bf16_f32 v0, v4, v161
	ds_write_b16 v160, v0 offset:1088
	v_cvt_pk_bf16_f32 v0, v5, v161
	ds_write_b16 v160, v0 offset:1216
	v_cvt_pk_bf16_f32 v0, v6, v161
	ds_write_b16 v160, v0 offset:1344
	v_cvt_pk_bf16_f32 v0, v7, v161
	ds_write_b16 v160, v0 offset:1472
	v_cvt_pk_bf16_f32 v0, v8, v161
	ds_write_b16 v160, v0 offset:2112
	v_cvt_pk_bf16_f32 v0, v9, v161
	ds_write_b16 v160, v0 offset:2240
	v_cvt_pk_bf16_f32 v0, v10, v161
	ds_write_b16 v160, v0 offset:2368
	v_cvt_pk_bf16_f32 v0, v11, v161
	s_lshl_b32 s0, s92, 5
	ds_write_b16 v160, v0 offset:2496
	v_cvt_pk_bf16_f32 v0, v12, v161
	s_or_b32 s0, s0, s88
	ds_write_b16 v160, v0 offset:3136
	v_cvt_pk_bf16_f32 v0, v13, v161
	s_ashr_i32 s1, s0, 31
	ds_write_b16 v160, v0 offset:3264
	v_cvt_pk_bf16_f32 v0, v14, v161
	v_and_b32_e32 v2, 64, v188
	s_lshl_b64 vcc, s[0:1], 12
	ds_write_b16 v160, v0 offset:3392
	v_cvt_pk_bf16_f32 v0, v15, v161
	v_xor_b32_e32 v3, 1, v188
	v_add_u32_e32 v4, 64, v2
	ds_write_b16 v160, v0 offset:3520
	v_lshl_add_u64 v[0:1], v[150:151], 0, vcc
	v_cmp_lt_i32_e32 vcc, v3, v4
	s_waitcnt lgkmcnt(0)
	v_lshl_add_u64 v[8:9], v[0:1], 0, v[134:135]
	s_lshl_b64 s[0:1], s[0:1], 3
	v_cndmask_b32_e32 v3, v188, v3, vcc
	v_lshlrev_b32_e32 v190, 2, v3
	v_xor_b32_e32 v3, 2, v188
	v_cmp_lt_i32_e32 vcc, v3, v4
	s_add_u32 s0, s54, s0
	s_addc_u32 s1, s55, s1
	v_cndmask_b32_e32 v3, v188, v3, vcc
	v_lshlrev_b32_e32 v191, 2, v3
	v_xor_b32_e32 v3, 4, v188
	v_cmp_lt_i32_e32 vcc, v3, v4
	ds_read_b128 v[4:7], v172
	s_waitcnt lgkmcnt(0)
	global_store_dwordx4 v[8:9], v[4:7], off offset:2048 nt
	v_cndmask_b32_e32 v3, v188, v3, vcc
	v_lshlrev_b32_e32 v192, 2, v3
	v_lshlrev_b32_e32 v3, 16, v4
	v_and_b32_e32 v4, 0xffff0000, v4
	v_mul_f32_e32 v4, v4, v4
	v_fmac_f32_e32 v4, v3, v3
	v_lshlrev_b32_e32 v3, 16, v5
	v_and_b32_e32 v5, 0xffff0000, v5
	v_mul_f32_e32 v5, v5, v5
	v_fmac_f32_e32 v5, v3, v3
	v_add_f32_e32 v3, v4, v5
	v_and_b32_e32 v5, 0xffff0000, v6
	v_lshlrev_b32_e32 v4, 16, v6
	v_mul_f32_e32 v5, v5, v5
	v_fmac_f32_e32 v5, v4, v4
	v_add_f32_e32 v3, v5, v3
	v_and_b32_e32 v5, 0xffff0000, v7
	v_lshlrev_b32_e32 v4, 16, v7
	v_mul_f32_e32 v5, v5, v5
	v_fmac_f32_e32 v5, v4, v4
	v_add_f32_e32 v3, v5, v3
	ds_bpermute_b32 v4, v190, v3
	s_waitcnt lgkmcnt(0)
	v_add_f32_e32 v3, v3, v4
	ds_bpermute_b32 v4, v191, v3
	s_waitcnt lgkmcnt(0)
	v_add_f32_e32 v3, v3, v4
	ds_bpermute_b32 v4, v192, v3
	s_and_saveexec_b64 vcc, s[6:7]
	s_cbranch_execz .LBB0_437
	v_lshl_add_u64 v[6:7], v[136:137], 2, s[0:1]
	s_waitcnt lgkmcnt(0)
	v_add_f32_e32 v3, v3, v4
	global_atomic_add_f32 v[6:7], v3, off offset:4
.LBB0_437:
	s_or_b64 exec, exec, vcc
	s_waitcnt lgkmcnt(0)
	ds_read_b128 v[4:7], v173
	v_lshl_add_u64 v[8:9], v[0:1], 0, v[138:139]
	s_waitcnt lgkmcnt(0)
	global_store_dwordx4 v[8:9], v[4:7], off offset:2048 nt
	v_lshlrev_b32_e32 v3, 16, v4
	s_nop 0
	v_and_b32_e32 v4, 0xffff0000, v4
	v_mul_f32_e32 v4, v4, v4
	v_fmac_f32_e32 v4, v3, v3
	v_lshlrev_b32_e32 v3, 16, v5
	v_and_b32_e32 v5, 0xffff0000, v5
	v_mul_f32_e32 v5, v5, v5
	v_fmac_f32_e32 v5, v3, v3
	v_add_f32_e32 v3, v4, v5
	v_and_b32_e32 v5, 0xffff0000, v6
	v_lshlrev_b32_e32 v4, 16, v6
	v_mul_f32_e32 v5, v5, v5
	v_fmac_f32_e32 v5, v4, v4
	v_add_f32_e32 v3, v5, v3
	v_and_b32_e32 v5, 0xffff0000, v7
	v_lshlrev_b32_e32 v4, 16, v7
	v_mul_f32_e32 v5, v5, v5
	v_fmac_f32_e32 v5, v4, v4
	v_add_f32_e32 v3, v5, v3
	ds_bpermute_b32 v4, v190, v3
	s_waitcnt lgkmcnt(0)
	v_add_f32_e32 v3, v3, v4
	ds_bpermute_b32 v4, v191, v3
	s_waitcnt lgkmcnt(0)
	v_add_f32_e32 v3, v3, v4
	ds_bpermute_b32 v4, v192, v3
	s_and_saveexec_b64 vcc, s[6:7]
	s_cbranch_execz .LBB0_439
	v_lshl_add_u64 v[6:7], v[140:141], 2, s[0:1]
	s_waitcnt lgkmcnt(0)
	v_add_f32_e32 v3, v3, v4
	global_atomic_add_f32 v[6:7], v3, off offset:4
.LBB0_439:
	s_or_b64 exec, exec, vcc
	s_waitcnt lgkmcnt(0)
	ds_read_b128 v[4:7], v174
	v_lshl_add_u64 v[8:9], v[0:1], 0, v[142:143]
	s_waitcnt lgkmcnt(0)
	global_store_dwordx4 v[8:9], v[4:7], off offset:2048 nt
	v_lshlrev_b32_e32 v3, 16, v4
	s_nop 0
	v_and_b32_e32 v4, 0xffff0000, v4
	v_mul_f32_e32 v4, v4, v4
	v_fmac_f32_e32 v4, v3, v3
	v_lshlrev_b32_e32 v3, 16, v5
	v_and_b32_e32 v5, 0xffff0000, v5
	v_mul_f32_e32 v5, v5, v5
	v_fmac_f32_e32 v5, v3, v3
	v_add_f32_e32 v3, v4, v5
	v_and_b32_e32 v5, 0xffff0000, v6
	v_lshlrev_b32_e32 v4, 16, v6
	v_mul_f32_e32 v5, v5, v5
	v_fmac_f32_e32 v5, v4, v4
	v_add_f32_e32 v3, v5, v3
	v_and_b32_e32 v5, 0xffff0000, v7
	v_lshlrev_b32_e32 v4, 16, v7
	v_mul_f32_e32 v5, v5, v5
	v_fmac_f32_e32 v5, v4, v4
	v_add_f32_e32 v3, v5, v3
	ds_bpermute_b32 v4, v190, v3
	s_waitcnt lgkmcnt(0)
	v_add_f32_e32 v3, v3, v4
	ds_bpermute_b32 v4, v191, v3
	s_waitcnt lgkmcnt(0)
	v_add_f32_e32 v3, v3, v4
	ds_bpermute_b32 v4, v192, v3
	s_and_saveexec_b64 vcc, s[6:7]
	s_cbranch_execz .LBB0_441
	v_lshl_add_u64 v[6:7], v[144:145], 2, s[0:1]
	s_waitcnt lgkmcnt(0)
	v_add_f32_e32 v3, v3, v4
	global_atomic_add_f32 v[6:7], v3, off offset:4
.LBB0_441:
	s_or_b64 exec, exec, vcc
	s_waitcnt lgkmcnt(0)
	ds_read_b128 v[4:7], v175
	v_lshl_add_u64 v[0:1], v[0:1], 0, v[146:147]
	s_waitcnt lgkmcnt(0)
	global_store_dwordx4 v[0:1], v[4:7], off offset:2048 nt
	v_and_b32_e32 v1, 0xffff0000, v4
	v_lshlrev_b32_e32 v0, 16, v4
	v_mul_f32_e32 v1, v1, v1
	v_and_b32_e32 v3, 0xffff0000, v5
	v_fmac_f32_e32 v1, v0, v0
	v_lshlrev_b32_e32 v0, 16, v5
	v_mul_f32_e32 v3, v3, v3
	v_fmac_f32_e32 v3, v0, v0
	v_add_f32_e32 v0, v1, v3
	v_and_b32_e32 v3, 0xffff0000, v6
	v_lshlrev_b32_e32 v1, 16, v6
	v_mul_f32_e32 v3, v3, v3
	v_fmac_f32_e32 v3, v1, v1
	v_add_f32_e32 v0, v3, v0
	v_and_b32_e32 v3, 0xffff0000, v7
	v_lshlrev_b32_e32 v1, 16, v7
	v_mul_f32_e32 v3, v3, v3
	v_fmac_f32_e32 v3, v1, v1
	v_add_f32_e32 v0, v3, v0
	ds_bpermute_b32 v1, v190, v0
	s_waitcnt lgkmcnt(0)
	v_add_f32_e32 v0, v0, v1
	ds_bpermute_b32 v1, v191, v0
	s_waitcnt lgkmcnt(0)
	v_add_f32_e32 v0, v0, v1
	ds_bpermute_b32 v1, v192, v0
	s_and_saveexec_b64 vcc, s[6:7]
	s_cbranch_execz .LBB0_423
	v_lshl_add_u64 v[4:5], v[148:149], 2, s[0:1]
	s_waitcnt lgkmcnt(0)
	v_add_f32_e32 v0, v0, v1
	global_atomic_add_f32 v[4:5], v0, off offset:4
	s_branch .LBB0_423
.LBB0_443:
	s_lshl_b32 s0, s63, 2
	v_mov_b32_e32 v0, s0
	s_add_i32 s0, s63, 1
	s_lshr_b32 s1, s63, 2
	global_load_dword v3, v0, s[74:75]
	v_cvt_f32_ubyte0_e32 v0, s0
	s_or_b32 s0, s1, s89
	s_ashr_i32 s1, s0, 31
	s_lshl_b32 s56, s33, 1
	s_waitcnt lgkmcnt(0)
	v_mbcnt_lo_u32_b32 v1, -1, 0
	v_mbcnt_hi_u32_b32 v1, -1, v1
	s_lshl_b64 s[0:1], s[0:1], 18
	v_and_b32_e32 v193, 31, v1
	v_mul_f32_e32 v0, -0.5, v0
	v_or_b32_e32 v6, s88, v193
	s_add_u32 s6, s52, s0
	v_exp_f32_e32 v12, v0
	v_lshlrev_b32_e32 v0, 3, v1
	v_ashrrev_i32_e32 v7, 31, v6
	s_addc_u32 s7, s53, s1
	v_ashrrev_i32_e32 v5, 5, v1
	v_cmp_gt_u32_e32 vcc, 32, v1
	v_lshlrev_b32_e32 v13, 4, v1
	v_ashrrev_i32_e32 v4, 3, v1
	v_and_b32_e32 v14, 7, v1
	v_ashrrev_i32_e32 v1, 31, v0
	v_lshlrev_b64 v[6:7], 12, v[6:7]
	s_add_u32 s0, s58, s0
	v_lshlrev_b32_e32 v8, 3, v5
	v_lshlrev_b64 v[0:1], 1, v[0:1]
	v_lshl_add_u64 v[6:7], s[48:49], 0, v[6:7]
	s_addc_u32 s1, s59, s1
	v_ashrrev_i32_e32 v9, 31, v8
	v_lshl_add_u64 v[6:7], v[6:7], 0, s[56:57]
	s_add_u32 s4, s6, s60
	v_lshl_add_u64 v[162:163], s[0:1], 0, v[0:1]
	s_mov_b32 s63, s57
	v_lshl_add_u64 v[164:165], v[8:9], 1, v[6:7]
	s_addc_u32 s5, s7, 0
	v_lshl_add_u64 v[6:7], v[162:163], 0, s[60:61]
	v_lshl_add_u64 v[8:9], v[164:165], 0, s[62:63]
	v_lshl_add_u64 v[10:11], s[4:5], 0, v[0:1]
	global_load_dwordx4 v[104:107], v[6:7], off
	global_load_dwordx4 v[108:111], v[6:7], off offset:1024
	global_load_dwordx4 v[116:119], v[6:7], off offset:2048
	global_load_dwordx4 v[120:123], v[6:7], off offset:3072
	global_load_dwordx4 v[80:83], v[8:9], off nt
	global_load_dwordx4 v[84:87], v[8:9], off offset:32 nt
	global_load_dwordx4 v[88:91], v[8:9], off offset:64 nt
	global_load_dwordx4 v[92:95], v[8:9], off offset:96 nt
	global_load_dwordx4 v[96:99], v[10:11], off
	global_load_dwordx4 v[100:103], v[10:11], off offset:1024
	global_load_dwordx4 v[112:115], v[10:11], off offset:2048
	global_load_dwordx4 v[124:127], v[10:11], off offset:3072
	v_lshlrev_b32_e32 v195, 2, v5
	v_lshlrev_b32_e32 v160, 4, v14
	v_add_u32_e32 v6, 8, v4
	v_lshl_add_u64 v[176:177], s[6:7], 0, v[0:1]
	v_add_u32_e32 v1, 8, v195
	v_ashrrev_i32_e32 v5, 31, v4
	v_add_u32_e32 v16, s3, v160
	v_lshl_add_u64 v[168:169], s[94:95], 0, v[160:161]
	v_ashrrev_i32_e32 v7, 31, v6
	v_and_or_b32 v1, v1, 60, v2
	v_cmp_eq_u32_e64 s[4:5], 0, v14
	v_lshlrev_b32_e32 v14, 7, v4
	v_lshlrev_b32_e32 v166, 1, v4
	v_add_u32_e32 v8, 16, v4
	v_add_u32_e32 v10, 24, v4
	v_lshlrev_b64 v[170:171], 12, v[4:5]
	v_lshlrev_b32_e32 v4, 7, v6
	v_lshlrev_b32_e32 v172, 1, v6
	v_lshlrev_b64 v[178:179], 12, v[6:7]
	v_add_u32_e32 v6, 10, v195
	v_lshlrev_b32_e32 v201, 2, v1
	v_ashrrev_i32_e32 v9, 31, v8
	v_add_u32_e32 v7, 11, v195
	v_lshlrev_b32_e32 v5, 7, v8
	v_lshlrev_b32_e32 v174, 1, v8
	v_lshlrev_b64 v[180:181], 12, v[8:9]
	v_add_u32_e32 v8, 16, v195
	v_ashrrev_i32_e32 v11, 31, v10
	v_add_u32_e32 v9, 17, v195
	v_lshlrev_b32_e32 v0, 7, v10
	v_lshlrev_b64 v[184:185], 12, v[10:11]
	v_lshlrev_b32_e32 v186, 1, v10
	v_add_u32_e32 v10, 18, v195
	v_add_u32_e32 v11, 19, v195
	v_mul_f32_e32 v182, 0x3fb8aa3b, v12
	v_add_u32_e32 v12, 24, v195
	v_add_u32_e32 v17, 25, v195
	v_add_u32_e32 v18, 26, v195
	v_add_u32_e32 v19, 27, v195
	v_and_or_b32 v20, v195, 60, v2
	v_lshl_add_u32 v15, v193, 1, s3
	v_and_b32_e32 v13, 0xfffffe00, v13
	s_waitcnt vmcnt(12)
	v_mul_f32_e32 v160, 0x3fb8aa3b, v3
	v_add_u32_e32 v3, 9, v195
	v_and_or_b32 v1, v3, 61, v2
	v_lshlrev_b32_e32 v202, 2, v1
	v_and_or_b32 v1, v6, 62, v2
	v_lshlrev_b32_e32 v203, 2, v1
	v_and_or_b32 v1, v7, 63, v2
	v_lshlrev_b32_e32 v204, 2, v1
	v_and_or_b32 v1, v8, 60, v2
	v_lshlrev_b32_e32 v205, 2, v1
	v_and_or_b32 v1, v9, 61, v2
	v_lshlrev_b32_e32 v206, 2, v1
	v_and_or_b32 v1, v10, 62, v2
	v_lshlrev_b32_e32 v207, 2, v1
	v_and_or_b32 v1, v11, 63, v2
	v_lshlrev_b32_e32 v208, 2, v1
	v_and_or_b32 v1, v12, 60, v2
	v_lshlrev_b32_e32 v209, 2, v1
	v_and_or_b32 v1, v17, 61, v2
	v_lshlrev_b32_e32 v210, 2, v1
	v_and_or_b32 v1, v18, 62, v2
	v_lshlrev_b32_e32 v197, 2, v20
	v_lshlrev_b32_e32 v211, 2, v1
	v_and_or_b32 v1, v19, 63, v2
	s_mov_b32 s8, 0
	v_cndmask_b32_e64 v194, 0, 1.0, vcc
	v_ashrrev_i32_e32 v167, 31, v166
	v_ashrrev_i32_e32 v173, 31, v172
	v_ashrrev_i32_e32 v175, 31, v174
	v_ashrrev_i32_e32 v187, 31, v186
	v_or_b32_e32 v198, 4, v197
	v_or_b32_e32 v199, 8, v197
	v_or_b32_e32 v200, 12, v197
	v_lshlrev_b32_e32 v212, 2, v1
	v_mov_b32_e32 v183, v182
	v_add_u32_e32 v213, v15, v13
	v_add_u32_e32 v214, v16, v14
	v_add_u32_e32 v215, v16, v4
	v_add_u32_e32 v216, v16, v5
	v_add_u32_e32 v217, v16, v0
	s_branch .LBB0_445

.LBB0_459:
	v_mov_b32_e32 v32, v219
	s_nop 1
	v_permlane32_swap_b32_e32 v219, v32
	v_add_f32_e32 v32, v219, v32
	v_div_scale_f32 v33, s[0:1], v32, v32, 1.0
	v_rcp_f32_e32 v34, v33
	s_cmp_eq_u32 s8, 7
	v_fma_f32 v35, -v33, v34, 1.0
	v_fmac_f32_e32 v34, v35, v34
	v_div_scale_f32 v35, vcc, 1.0, v32, 1.0
	v_mul_f32_e32 v36, v35, v34
	v_fma_f32 v37, -v33, v36, v35
	v_fmac_f32_e32 v36, v37, v34
	v_fma_f32 v33, -v33, v36, v35
	v_div_fmas_f32 v33, v33, v34, v36
	v_div_fixup_f32 v32, v33, v32, 1.0
	ds_bpermute_b32 v47, v197, v32
	ds_bpermute_b32 v46, v198, v32
	ds_bpermute_b32 v45, v199, v32
	ds_bpermute_b32 v44, v200, v32
	ds_bpermute_b32 v43, v201, v32
	ds_bpermute_b32 v42, v202, v32
	ds_bpermute_b32 v41, v203, v32
	ds_bpermute_b32 v40, v204, v32
	ds_bpermute_b32 v39, v205, v32
	ds_bpermute_b32 v38, v206, v32
	ds_bpermute_b32 v37, v207, v32
	ds_bpermute_b32 v36, v208, v32
	ds_bpermute_b32 v35, v209, v32
	ds_bpermute_b32 v34, v210, v32
	ds_bpermute_b32 v33, v211, v32
	ds_bpermute_b32 v32, v212, v32
	s_cbranch_scc1 .LBB0_461
	s_add_i32 s10, s10, 8
	s_and_b32 s10, s10, 0x70
	s_and_b64 s[0:1], s[6:7], exec
	s_cselect_b32 s0, s86, s43
	s_or_b32 s0, s10, s0
	s_lshl_b32 s56, s0, 17
	v_lshl_add_u64 v[48:49], v[164:165], 0, s[56:57]
	s_lshl_b32 s56, s0, 12
	global_load_dwordx4 v[80:83], v[48:49], off nt
	global_load_dwordx4 v[84:87], v[48:49], off offset:32 nt
	global_load_dwordx4 v[88:91], v[48:49], off offset:64 nt
	global_load_dwordx4 v[92:95], v[48:49], off offset:96 nt
	v_lshl_add_u64 v[48:49], v[176:177], 0, s[56:57]
	global_load_dwordx4 v[96:99], v[48:49], off
	global_load_dwordx4 v[100:103], v[48:49], off offset:1024
	global_load_dwordx4 v[112:115], v[48:49], off offset:2048
	global_load_dwordx4 v[124:127], v[48:49], off offset:3072
	v_lshl_add_u64 v[48:49], v[162:163], 0, s[56:57]
	global_load_dwordx4 v[104:107], v[48:49], off
	global_load_dwordx4 v[108:111], v[48:49], off offset:1024
	global_load_dwordx4 v[116:119], v[48:49], off offset:2048
	global_load_dwordx4 v[120:123], v[48:49], off offset:3072
.LBB0_461:
	s_waitcnt lgkmcnt(14)
	v_mul_f32_e32 v0, v0, v47
	v_cvt_pk_bf16_f32 v0, v0, v161
	v_mul_f32_e32 v1, v1, v46
	ds_write_b16 v213, v0
	v_cvt_pk_bf16_f32 v0, v1, v161
	s_waitcnt lgkmcnt(14)
	v_mul_f32_e32 v2, v2, v45
	ds_write_b16 v213, v0 offset:128
	v_cvt_pk_bf16_f32 v0, v2, v161
	s_waitcnt lgkmcnt(14)
	v_mul_f32_e32 v3, v3, v44
	ds_write_b16 v213, v0 offset:256
	v_cvt_pk_bf16_f32 v0, v3, v161
	s_waitcnt lgkmcnt(14)
	v_mul_f32_e32 v4, v4, v43
	ds_write_b16 v213, v0 offset:384
	v_cvt_pk_bf16_f32 v0, v4, v161
	s_waitcnt lgkmcnt(14)
	v_mul_f32_e32 v5, v5, v42
	ds_write_b16 v213, v0 offset:1024
	v_cvt_pk_bf16_f32 v0, v5, v161
	s_waitcnt lgkmcnt(14)
	v_mul_f32_e32 v6, v6, v41
	ds_write_b16 v213, v0 offset:1152
	v_cvt_pk_bf16_f32 v0, v6, v161
	s_waitcnt lgkmcnt(14)
	v_mul_f32_e32 v7, v7, v40
	ds_write_b16 v213, v0 offset:1280
	v_cvt_pk_bf16_f32 v0, v7, v161
	s_waitcnt lgkmcnt(14)
	v_mul_f32_e32 v8, v8, v39
	ds_write_b16 v213, v0 offset:1408
	v_cvt_pk_bf16_f32 v0, v8, v161
	s_waitcnt lgkmcnt(14)
	v_mul_f32_e32 v9, v9, v38
	ds_write_b16 v213, v0 offset:2048
	v_cvt_pk_bf16_f32 v0, v9, v161
	s_waitcnt lgkmcnt(14)
	v_mul_f32_e32 v10, v10, v37
	ds_write_b16 v213, v0 offset:2176
	v_cvt_pk_bf16_f32 v0, v10, v161
	s_waitcnt lgkmcnt(14)
	v_mul_f32_e32 v11, v11, v36
	ds_write_b16 v213, v0 offset:2304
	v_cvt_pk_bf16_f32 v0, v11, v161
	s_waitcnt lgkmcnt(14)
	v_mul_f32_e32 v12, v12, v35
	ds_write_b16 v213, v0 offset:2432
	v_cvt_pk_bf16_f32 v0, v12, v161
	s_waitcnt lgkmcnt(14)
	v_mul_f32_e32 v13, v13, v34
	ds_write_b16 v213, v0 offset:3072
	v_cvt_pk_bf16_f32 v0, v13, v161
	s_waitcnt lgkmcnt(14)
	v_mul_f32_e32 v14, v14, v33
	ds_write_b16 v213, v0 offset:3200
	v_cvt_pk_bf16_f32 v0, v14, v161
	s_waitcnt lgkmcnt(14)
	v_mul_f32_e32 v15, v15, v32
	ds_write_b16 v213, v0 offset:3328
	v_cvt_pk_bf16_f32 v0, v15, v161
	v_mul_f32_e32 v16, v16, v47
	ds_write_b16 v213, v0 offset:3456
	v_cvt_pk_bf16_f32 v0, v16, v161
	v_mul_f32_e32 v17, v17, v46
	ds_write_b16 v213, v0 offset:64
	v_cvt_pk_bf16_f32 v0, v17, v161
	v_mul_f32_e32 v18, v18, v45
	ds_write_b16 v213, v0 offset:192
	v_cvt_pk_bf16_f32 v0, v18, v161
	v_mul_f32_e32 v19, v19, v44
	ds_write_b16 v213, v0 offset:320
	v_cvt_pk_bf16_f32 v0, v19, v161
	v_mul_f32_e32 v20, v20, v43
	ds_write_b16 v213, v0 offset:448
	v_cvt_pk_bf16_f32 v0, v20, v161
	v_mul_f32_e32 v21, v21, v42
	ds_write_b16 v213, v0 offset:1088
	v_cvt_pk_bf16_f32 v0, v21, v161
	v_mul_f32_e32 v22, v22, v41
	ds_write_b16 v213, v0 offset:1216
	v_cvt_pk_bf16_f32 v0, v22, v161
	v_mul_f32_e32 v23, v23, v40
	ds_write_b16 v213, v0 offset:1344
	v_cvt_pk_bf16_f32 v0, v23, v161
	v_mul_f32_e32 v24, v24, v39
	ds_write_b16 v213, v0 offset:1472
	v_cvt_pk_bf16_f32 v0, v24, v161
	v_mul_f32_e32 v25, v25, v38
	ds_write_b16 v213, v0 offset:2112
	v_cvt_pk_bf16_f32 v0, v25, v161
	v_mul_f32_e32 v26, v26, v37
	ds_write_b16 v213, v0 offset:2240
	v_cvt_pk_bf16_f32 v0, v26, v161
	v_mul_f32_e32 v27, v27, v36
	ds_write_b16 v213, v0 offset:2368
	v_cvt_pk_bf16_f32 v0, v27, v161
	v_mul_f32_e32 v28, v28, v35
	ds_write_b16 v213, v0 offset:2496
	v_cvt_pk_bf16_f32 v0, v28, v161
	v_mul_f32_e32 v29, v29, v34
	ds_write_b16 v213, v0 offset:3136
	v_cvt_pk_bf16_f32 v0, v29, v161
	v_mul_f32_e32 v30, v30, v33
	ds_write_b16 v213, v0 offset:3264
	v_cvt_pk_bf16_f32 v0, v30, v161
	v_mul_f32_e32 v31, v31, v32
	ds_write_b16 v213, v0 offset:3392
	v_cvt_pk_bf16_f32 v0, v31, v161
	ds_write_b16 v213, v0 offset:3520
	s_waitcnt lgkmcnt(0)
	ds_read_b128 v[4:7], v214
	s_or_b32 s0, s9, s88
	s_ashr_i32 s1, s0, 31
	s_lshl_b64 s[6:7], s[0:1], 12
	s_lshl_b64 s[0:1], s[0:1], 3
	s_waitcnt lgkmcnt(0)
	v_and_b32_e32 v1, 0xffff0000, v4
	v_lshlrev_b32_e32 v0, 16, v4
	v_mul_f32_e32 v1, v1, v1
	v_and_b32_e32 v2, 0xffff0000, v5
	v_fmac_f32_e32 v1, v0, v0
	v_lshlrev_b32_e32 v0, 16, v5
	v_mul_f32_e32 v2, v2, v2
	v_fmac_f32_e32 v2, v0, v0
	v_add_f32_e32 v0, v1, v2
	v_and_b32_e32 v2, 0xffff0000, v6
	v_lshlrev_b32_e32 v1, 16, v6
	v_mul_f32_e32 v2, v2, v2
	v_fmac_f32_e32 v2, v1, v1
	v_add_f32_e32 v0, v2, v0
	v_and_b32_e32 v2, 0xffff0000, v7
	v_lshlrev_b32_e32 v1, 16, v7
	v_mul_f32_e32 v2, v2, v2
	v_fmac_f32_e32 v2, v1, v1
	v_add_f32_e32 v0, v2, v0
	ds_bpermute_b32 v1, v190, v0
	s_add_u32 s0, s54, s0
	s_addc_u32 s1, s55, s1
	s_waitcnt lgkmcnt(0)
	v_add_f32_e32 v0, v0, v1
	ds_bpermute_b32 v1, v191, v0
	s_waitcnt lgkmcnt(0)
	v_add_f32_e32 v2, v0, v1
	ds_bpermute_b32 v3, v192, v2
	v_lshl_add_u64 v[0:1], v[168:169], 0, s[6:7]
	v_lshl_add_u64 v[8:9], v[0:1], 0, v[170:171]
	global_store_dwordx4 v[8:9], v[4:7], off nt
	s_and_saveexec_b64 s[6:7], s[4:5]
	s_cbranch_execz .LBB0_463
	v_lshl_add_u64 v[4:5], v[166:167], 2, s[0:1]
	s_waitcnt lgkmcnt(0)
	v_add_f32_e32 v2, v2, v3
	global_atomic_add_f32 v[4:5], v2, off
.LBB0_463:
	s_or_b64 exec, exec, s[6:7]
	ds_read_b128 v[4:7], v215
	s_waitcnt lgkmcnt(0)
	v_and_b32_e32 v3, 0xffff0000, v4
	v_and_b32_e32 v9, 0xffff0000, v5
	v_lshlrev_b32_e32 v2, 16, v4
	v_lshlrev_b32_e32 v8, 16, v5
	v_mul_f32_e32 v3, v3, v3
	v_mul_f32_e32 v9, v9, v9
	v_fmac_f32_e32 v3, v2, v2
	v_fmac_f32_e32 v9, v8, v8
	v_and_b32_e32 v8, 0xffff0000, v6
	v_add_f32_e32 v2, v3, v9
	v_lshlrev_b32_e32 v3, 16, v6
	v_mul_f32_e32 v8, v8, v8
	v_fmac_f32_e32 v8, v3, v3
	v_add_f32_e32 v2, v8, v2
	v_and_b32_e32 v8, 0xffff0000, v7
	v_lshlrev_b32_e32 v3, 16, v7
	v_mul_f32_e32 v8, v8, v8
	v_fmac_f32_e32 v8, v3, v3
	v_add_f32_e32 v2, v8, v2
	ds_bpermute_b32 v3, v190, v2
	v_lshl_add_u64 v[8:9], v[0:1], 0, v[178:179]
	global_store_dwordx4 v[8:9], v[4:7], off nt
	s_waitcnt lgkmcnt(0)
	v_add_f32_e32 v2, v2, v3
	ds_bpermute_b32 v3, v191, v2
	s_waitcnt lgkmcnt(0)
	v_add_f32_e32 v2, v2, v3
	ds_bpermute_b32 v3, v192, v2
	s_and_saveexec_b64 s[6:7], s[4:5]
	s_cbranch_execz .LBB0_465
	v_lshl_add_u64 v[4:5], v[172:173], 2, s[0:1]
	s_waitcnt lgkmcnt(0)
	v_add_f32_e32 v2, v2, v3
	global_atomic_add_f32 v[4:5], v2, off
.LBB0_465:
	s_or_b64 exec, exec, s[6:7]
	ds_read_b128 v[4:7], v216
	s_waitcnt lgkmcnt(0)
	v_and_b32_e32 v3, 0xffff0000, v4
	v_and_b32_e32 v9, 0xffff0000, v5
	v_lshlrev_b32_e32 v2, 16, v4
	v_lshlrev_b32_e32 v8, 16, v5
	v_mul_f32_e32 v3, v3, v3
	v_mul_f32_e32 v9, v9, v9
	v_fmac_f32_e32 v3, v2, v2
	v_fmac_f32_e32 v9, v8, v8
	v_and_b32_e32 v8, 0xffff0000, v6
	v_add_f32_e32 v2, v3, v9
	v_lshlrev_b32_e32 v3, 16, v6
	v_mul_f32_e32 v8, v8, v8
	v_fmac_f32_e32 v8, v3, v3
	v_add_f32_e32 v2, v8, v2
	v_and_b32_e32 v8, 0xffff0000, v7
	v_lshlrev_b32_e32 v3, 16, v7
	v_mul_f32_e32 v8, v8, v8
	v_fmac_f32_e32 v8, v3, v3
	v_add_f32_e32 v2, v8, v2
	ds_bpermute_b32 v3, v190, v2
	v_lshl_add_u64 v[8:9], v[0:1], 0, v[180:181]
	global_store_dwordx4 v[8:9], v[4:7], off nt
	s_waitcnt lgkmcnt(0)
	v_add_f32_e32 v2, v2, v3
	ds_bpermute_b32 v3, v191, v2
	s_waitcnt lgkmcnt(0)
	v_add_f32_e32 v2, v2, v3
	ds_bpermute_b32 v3, v192, v2
	s_and_saveexec_b64 s[6:7], s[4:5]
	s_cbranch_execz .LBB0_467
	v_lshl_add_u64 v[4:5], v[174:175], 2, s[0:1]
	s_waitcnt lgkmcnt(0)
	v_add_f32_e32 v2, v2, v3
	global_atomic_add_f32 v[4:5], v2, off
.LBB0_467:
	s_or_b64 exec, exec, s[6:7]
	ds_read_b128 v[4:7], v217
	v_lshl_add_u64 v[0:1], v[0:1], 0, v[184:185]
	s_waitcnt lgkmcnt(0)
	v_and_b32_e32 v3, 0xffff0000, v4
	v_and_b32_e32 v9, 0xffff0000, v5
	v_lshlrev_b32_e32 v2, 16, v4
	v_lshlrev_b32_e32 v8, 16, v5
	v_mul_f32_e32 v3, v3, v3
	v_mul_f32_e32 v9, v9, v9
	v_fmac_f32_e32 v3, v2, v2
	v_fmac_f32_e32 v9, v8, v8
	v_and_b32_e32 v8, 0xffff0000, v6
	v_add_f32_e32 v2, v3, v9
	v_lshlrev_b32_e32 v3, 16, v6
	v_mul_f32_e32 v8, v8, v8
	v_fmac_f32_e32 v8, v3, v3
	v_add_f32_e32 v2, v8, v2
	v_and_b32_e32 v8, 0xffff0000, v7
	v_lshlrev_b32_e32 v3, 16, v7
	v_mul_f32_e32 v8, v8, v8
	v_fmac_f32_e32 v8, v3, v3
	v_add_f32_e32 v2, v8, v2
	ds_bpermute_b32 v3, v190, v2
	global_store_dwordx4 v[0:1], v[4:7], off nt
	s_waitcnt lgkmcnt(0)
	v_add_f32_e32 v2, v2, v3
	ds_bpermute_b32 v3, v191, v2
	s_waitcnt lgkmcnt(0)
	v_add_f32_e32 v2, v2, v3
	ds_bpermute_b32 v3, v192, v2
	s_and_saveexec_b64 s[6:7], s[4:5]
	s_cbranch_execz .LBB0_444
	v_lshl_add_u64 v[0:1], v[186:187], 2, s[0:1]
	s_waitcnt lgkmcnt(0)
	v_add_f32_e32 v2, v2, v3
	global_atomic_add_f32 v[0:1], v2, off
	s_branch .LBB0_444
